# adaLN modulation GEMV: the wait for the first weight load moved below the 15 loads that follow it (counted wait), one memory latency per 16-row block instead of two
# speedup vs baseline: 1.0001x; 1.0001x over previous
; __device__ __forceinline__ void phase_mod(const Fr& F) {
;     ...
;         const float* wm = F.a->in[5] + (size_t)l * D * 3072 + n0 + F.lane;
;         float acc[5] = {0.f, 0.f, 0.f, 0.f, 0.f};
; #pragma unroll 16
;         for (int kk = 0; kk < 128; ++kk) { const int k = F.wave * 128 + kk; const float w = wm[(size_t)k * 3072];
; #pragma unroll
;             for (int j = 0; j < 5; ++j) acc[j] += sc[j * 1024 + k] * w; }
.LBB0_12:
	v_lshl_add_u64 v[14:15], v[8:9], 0, s[8:9]
	v_add_co_u32_e64 v102, s[6:7], s3, v14
	global_load_dword v100, v[14:15], off
	s_nop 0
	v_addc_co_u32_e64 v103, s[6:7], 0, v15, s[6:7]
	v_add_co_u32_e64 v104, s[6:7], s17, v14
	v_mov_b32_e32 v19, s45
	s_nop 0
	v_addc_co_u32_e64 v105, s[6:7], 0, v15, s[6:7]
	v_add_co_u32_e64 v106, s[6:7], s18, v14
	ds_read_b128 v[20:23], v19
	ds_read_b128 v[24:27], v19 offset:16
	v_addc_co_u32_e64 v107, s[6:7], 0, v15, s[6:7]
	v_add_co_u32_e64 v108, s[6:7], s19, v14
	ds_read_b128 v[28:31], v19 offset:4096
	ds_read_b128 v[32:35], v19 offset:4112
	ds_read_b128 v[36:39], v19 offset:8192
	ds_read_b128 v[40:43], v19 offset:8208
	ds_read_b128 v[44:47], v19 offset:12288
	ds_read_b128 v[48:51], v19 offset:12304
	v_addc_co_u32_e64 v109, s[6:7], 0, v15, s[6:7]
	v_add_co_u32_e64 v110, s[6:7], s20, v14
	ds_read_b128 v[52:55], v19 offset:16384
	ds_read_b128 v[56:59], v19 offset:16400
	v_addc_co_u32_e64 v111, s[6:7], 0, v15, s[6:7]
	v_add_co_u32_e64 v112, s[6:7], s21, v14
	ds_read_b128 v[60:63], v19 offset:32
	ds_read_b128 v[64:67], v19 offset:48
	ds_read_b128 v[68:71], v19 offset:4128
	ds_read_b128 v[72:75], v19 offset:4144
	ds_read_b128 v[76:79], v19 offset:8224
	ds_read_b128 v[80:83], v19 offset:8240
	ds_read_b128 v[84:87], v19 offset:12320
	ds_read_b128 v[88:91], v19 offset:12336
	ds_read_b128 v[92:95], v19 offset:16416
	ds_read_b128 v[96:99], v19 offset:16432
	v_addc_co_u32_e64 v113, s[6:7], 0, v15, s[6:7]
	v_add_co_u32_e64 v114, s[6:7], s22, v14
	s_add_u32 s8, s8, 0x30000
	s_nop 0
	v_addc_co_u32_e64 v115, s[6:7], 0, v15, s[6:7]
	v_add_co_u32_e64 v116, s[6:7], s23, v14
	s_addc_u32 s9, s9, 0
	s_nop 0
	v_addc_co_u32_e64 v117, s[6:7], 0, v15, s[6:7]
	v_add_co_u32_e64 v118, s[6:7], s24, v14
	s_add_i32 s45, s45, 64
	s_nop 0
	v_addc_co_u32_e64 v119, s[6:7], 0, v15, s[6:7]
	v_add_co_u32_e64 v120, s[6:7], s25, v14
	s_cmp_eq_u32 s8, 0x180000
	s_nop 0
	v_addc_co_u32_e64 v121, s[6:7], 0, v15, s[6:7]
	v_add_co_u32_e64 v122, s[6:7], s37, v14
	s_nop 1
	v_addc_co_u32_e64 v123, s[6:7], 0, v15, s[6:7]
	v_add_co_u32_e64 v124, s[6:7], s38, v14
	s_nop 1
	v_addc_co_u32_e64 v125, s[6:7], 0, v15, s[6:7]
	v_add_co_u32_e64 v126, s[6:7], s39, v14
	s_nop 1
	v_addc_co_u32_e64 v127, s[6:7], 0, v15, s[6:7]
	v_add_co_u32_e64 v132, s[6:7], s40, v14
	s_nop 1
	v_addc_co_u32_e64 v133, s[6:7], 0, v15, s[6:7]
	v_add_co_u32_e64 v14, s[6:7], s41, v14
	s_nop 1
	v_addc_co_u32_e64 v15, s[6:7], 0, v15, s[6:7]
	global_load_dword v102, v[102:103], off
	s_nop 0
	global_load_dword v104, v[104:105], off
	s_nop 0
	global_load_dword v106, v[106:107], off
	s_nop 0
	global_load_dword v108, v[108:109], off
	s_nop 0
	global_load_dword v134, v[110:111], off
	global_load_dword v136, v[112:113], off
	s_nop 0
	global_load_dword v110, v[114:115], off
	global_load_dword v112, v[116:117], off
	global_load_dword v138, v[118:119], off
	global_load_dword v140, v[120:121], off
	s_nop 0
	global_load_dword v114, v[122:123], off
	global_load_dword v116, v[124:125], off
	global_load_dword v118, v[126:127], off
	global_load_dword v120, v[132:133], off
	global_load_dword v142, v[14:15], off
	s_waitcnt vmcnt(15) lgkmcnt(11)
	v_fmac_f32_e32 v4, v100, v52
	v_mov_b32_e32 v14, v20
	v_mov_b32_e32 v15, v28
	v_mov_b32_e32 v28, v21
	v_mov_b32_e32 v20, v22
	v_mov_b32_e32 v21, v30
	v_mov_b32_e32 v30, v23
	v_mov_b32_e32 v22, v36
	v_mov_b32_e32 v23, v44
	v_mov_b32_e32 v44, v37
	v_pk_fma_f32 v[10:11], v[100:101], v[14:15], v[10:11] op_sel_hi:[0,1,1]
	v_pk_fma_f32 v[12:13], v[100:101], v[22:23], v[12:13] op_sel_hi:[0,1,1]
	v_mov_b32_e32 v36, v38
	v_mov_b32_e32 v37, v46
	v_mov_b32_e32 v46, v39
	v_mov_b32_e32 v38, v24
	v_mov_b32_e32 v39, v32
	v_mov_b32_e32 v32, v25
	v_mov_b32_e32 v24, v26
	v_mov_b32_e32 v25, v34
	v_mov_b32_e32 v34, v27
	v_mov_b32_e32 v26, v40
	v_mov_b32_e32 v27, v48
	v_mov_b32_e32 v48, v41
	v_mov_b32_e32 v40, v42
	v_mov_b32_e32 v41, v50
	v_mov_b32_e32 v50, v43
	s_waitcnt lgkmcnt(9)
	v_mov_b32_e32 v42, v60
	s_waitcnt lgkmcnt(7)
	v_mov_b32_e32 v43, v68
	v_mov_b32_e32 v68, v61
	v_mov_b32_e32 v60, v62
	v_mov_b32_e32 v61, v70
	v_mov_b32_e32 v70, v63
	s_waitcnt lgkmcnt(5)
	v_mov_b32_e32 v62, v76
	s_waitcnt lgkmcnt(3)
	v_mov_b32_e32 v63, v84
	v_mov_b32_e32 v84, v77
	v_mov_b32_e32 v76, v78
	v_mov_b32_e32 v77, v86
	v_mov_b32_e32 v86, v79
	v_mov_b32_e32 v78, v64
	v_mov_b32_e32 v79, v72
	v_mov_b32_e32 v72, v65
	v_mov_b32_e32 v64, v66
	v_mov_b32_e32 v65, v74
	v_mov_b32_e32 v74, v67
	v_mov_b32_e32 v66, v80
	s_waitcnt lgkmcnt(2)
;     __device__ __forceinline__ float* mod(int l) const { return (float*)(ws + OFF_MOD) + l * 5 * 3072; }
; __device__ __forceinline__ void phase_mod(const Fr& F) {
;     ...
;         for (int kk = 0; kk < 128; ++kk) { const int k = F.wave * 128 + kk; const float w = wm[(size_t)k * 3072];
; #pragma unroll
;             for (int j = 0; j < 5; ++j) acc[j] += sc[j * 1024 + k] * w; }
; #pragma unroll
;         for (int j = 0; j < 5; ++j) red[(F.wave * 5 + j) * 64 + F.lane] = acc[j];
;         __syncthreads();
;         if (F.tid < 320) { const int j = F.tid >> 6, ln = F.tid & 63; float s = F.a->in[6][l * 3072 + n0 + ln];
;             for (int w = 0; w < 8; ++w) s += red[(w * 5 + j) * 64 + ln];
;             F.mod(l)[j * 3072 + n0 + ln] = s; }
	v_mov_b32_e32 v67, v88
	v_mov_b32_e32 v88, v81
	v_mov_b32_e32 v80, v82
	v_mov_b32_e32 v81, v90
	v_mov_b32_e32 v90, v83
	s_waitcnt vmcnt(14)
	v_pk_fma_f32 v[10:11], v[102:103], v[28:29], v[10:11] op_sel_hi:[0,1,1]
	v_pk_fma_f32 v[12:13], v[102:103], v[44:45], v[12:13] op_sel_hi:[0,1,1]
	v_fmac_f32_e32 v4, v102, v53
	s_waitcnt vmcnt(13)
	v_pk_fma_f32 v[10:11], v[104:105], v[20:21], v[10:11] op_sel_hi:[0,1,1]
	v_pk_fma_f32 v[12:13], v[104:105], v[36:37], v[12:13] op_sel_hi:[0,1,1]
	v_fmac_f32_e32 v4, v104, v54
	s_waitcnt vmcnt(12)
	v_pk_fma_f32 v[10:11], v[106:107], v[30:31], v[10:11] op_sel_hi:[0,1,1]
	v_pk_fma_f32 v[12:13], v[106:107], v[46:47], v[12:13] op_sel_hi:[0,1,1]
	v_fmac_f32_e32 v4, v106, v55
	s_waitcnt vmcnt(11)
	v_pk_fma_f32 v[10:11], v[108:109], v[38:39], v[10:11] op_sel_hi:[0,1,1]
	v_pk_fma_f32 v[12:13], v[108:109], v[26:27], v[12:13] op_sel_hi:[0,1,1]
	v_fmac_f32_e32 v4, v108, v56
	s_waitcnt vmcnt(10)
	v_pk_fma_f32 v[10:11], v[134:135], v[32:33], v[10:11] op_sel_hi:[0,1,1]
	v_pk_fma_f32 v[12:13], v[134:135], v[48:49], v[12:13] op_sel_hi:[0,1,1]
	v_fmac_f32_e32 v4, v134, v57
	s_waitcnt vmcnt(9)
	v_pk_fma_f32 v[10:11], v[136:137], v[24:25], v[10:11] op_sel_hi:[0,1,1]
	v_pk_fma_f32 v[12:13], v[136:137], v[40:41], v[12:13] op_sel_hi:[0,1,1]
	v_fmac_f32_e32 v4, v136, v58
	s_waitcnt vmcnt(8)
	v_pk_fma_f32 v[10:11], v[110:111], v[34:35], v[10:11] op_sel_hi:[0,1,1]
	v_pk_fma_f32 v[12:13], v[110:111], v[50:51], v[12:13] op_sel_hi:[0,1,1]
	v_fmac_f32_e32 v4, v110, v59
	s_waitcnt vmcnt(7)
	v_pk_fma_f32 v[10:11], v[112:113], v[42:43], v[10:11] op_sel_hi:[0,1,1]
	v_pk_fma_f32 v[12:13], v[112:113], v[62:63], v[12:13] op_sel_hi:[0,1,1]
	s_waitcnt lgkmcnt(1)
	v_fmac_f32_e32 v4, v112, v92
	s_waitcnt vmcnt(6)
	v_pk_fma_f32 v[10:11], v[138:139], v[68:69], v[10:11] op_sel_hi:[0,1,1]
	v_pk_fma_f32 v[12:13], v[138:139], v[84:85], v[12:13] op_sel_hi:[0,1,1]
	v_fmac_f32_e32 v4, v138, v93
	s_waitcnt vmcnt(5)
	v_pk_fma_f32 v[10:11], v[140:141], v[60:61], v[10:11] op_sel_hi:[0,1,1]
	v_pk_fma_f32 v[12:13], v[140:141], v[76:77], v[12:13] op_sel_hi:[0,1,1]
	v_fmac_f32_e32 v4, v140, v94
	s_waitcnt vmcnt(4)
	v_pk_fma_f32 v[10:11], v[114:115], v[70:71], v[10:11] op_sel_hi:[0,1,1]
	v_pk_fma_f32 v[12:13], v[114:115], v[86:87], v[12:13] op_sel_hi:[0,1,1]
	v_fmac_f32_e32 v4, v114, v95
	s_waitcnt vmcnt(3)
	v_pk_fma_f32 v[10:11], v[116:117], v[78:79], v[10:11] op_sel_hi:[0,1,1]
	v_pk_fma_f32 v[12:13], v[116:117], v[66:67], v[12:13] op_sel_hi:[0,1,1]
	s_waitcnt lgkmcnt(0)
	v_fmac_f32_e32 v4, v116, v96
	s_waitcnt vmcnt(2)
	v_pk_fma_f32 v[10:11], v[118:119], v[72:73], v[10:11] op_sel_hi:[0,1,1]
	v_pk_fma_f32 v[12:13], v[118:119], v[88:89], v[12:13] op_sel_hi:[0,1,1]
	v_fmac_f32_e32 v4, v118, v97
	s_waitcnt vmcnt(1)
	v_pk_fma_f32 v[10:11], v[120:121], v[64:65], v[10:11] op_sel_hi:[0,1,1]
	v_pk_fma_f32 v[12:13], v[120:121], v[80:81], v[12:13] op_sel_hi:[0,1,1]
	v_fmac_f32_e32 v4, v120, v98
	s_waitcnt vmcnt(0)
	v_pk_fma_f32 v[10:11], v[142:143], v[74:75], v[10:11] op_sel_hi:[0,1,1]
	v_pk_fma_f32 v[12:13], v[142:143], v[90:91], v[12:13] op_sel_hi:[0,1,1]
	v_fmac_f32_e32 v4, v142, v99
	s_cbranch_scc0 .LBB0_12
	ds_write2st64_b32 v1, v10, v11 offset0:80 offset1:81
	ds_write2st64_b32 v1, v12, v13 offset0:82 offset1:83
	ds_write_b32 v1, v4 offset:21504
	s_waitcnt lgkmcnt(0)
	s_barrier
	s_and_saveexec_b64 s[6:7], vcc
	s_cbranch_execz .LBB0_10
	s_mul_i32 s8, s43, 0xffffffd0
	s_add_i32 s8, s8, s42
	s_lshl_b32 s45, s8, 6
	s_add_i32 s8, s45, s44
	v_or_b32_e32 v8, s8, v130
	v_ashrrev_i32_e32 v9, 31, v8
	v_lshl_add_u64 v[8:9], v[8:9], 2, s[10:11]
	global_load_dword v4, v[8:9], off
	ds_read2st64_b32 v[8:9], v16 offset0:85 offset1:90
	ds_read_b32 v19, v3 offset:20480
	ds_read_b32 v20, v17 offset:20480
	ds_read2st64_b32 v[10:11], v16 offset0:100 offset1:105
	ds_read2st64_b32 v[12:13], v16 offset0:110 offset1:115
	s_mul_i32 s8, s43, 0x3c00
	s_ashr_i32 s9, s8, 31
	s_lshl_b64 s[8:9], s[8:9], 2
	v_add_u32_e32 v14, s45, v18
	s_add_u32 s8, s26, s8
	v_ashrrev_i32_e32 v15, 31, v14
	s_addc_u32 s9, s27, s9
	s_waitcnt vmcnt(0) lgkmcnt(3)
	v_add_f32_e32 v4, v4, v19
	v_add_f32_e32 v4, v4, v8
	v_add_f32_e32 v4, v4, v9
	s_waitcnt lgkmcnt(2)
	v_add_f32_e32 v4, v4, v20
	s_waitcnt lgkmcnt(1)
	v_add_f32_e32 v4, v4, v10
	v_add_f32_e32 v4, v4, v11
	s_waitcnt lgkmcnt(0)
	v_add_f32_e32 v4, v4, v12
	v_add_f32_e32 v4, v4, v13
	v_lshl_add_u64 v[8:9], v[14:15], 2, s[8:9]
	global_store_dword v[8:9], v4, off
	s_branch .LBB0_10
